# all four staging waves host conversion slices (wave 4's transpose tile in the idle halo/rstd LDS area), counted wait leaves the stagers' prefetch in flight; scan converts 11,13,15,17,22,23,25,27; tail
# speedup vs baseline: 1.0108x; 1.0032x over previous
; #define GAS __attribute__((address_space(1)))
; __device__ __forceinline__ void rwkv_scan_phase(Frame& F, const bf16* RKV, const float* WAG, const bf16* AGB, const float* k_k, const float* k_a, const float* r_k, bf16* Y, float* BS, float* ST2) {
;     ...
;             const int st = tid - 256, ts = st >> 4, c4 = st & 15;
;             const f32x4 kkc = *(const GAS f32x4*)(k_k + h * 64 + 4 * c4), kac = *(const GAS f32x4*)(k_a + h * 64 + 4 * c4), rkc = *(const GAS f32x4*)(r_k + h * 64 + 4 * c4);
;     ...
;             constexpr int NCH = SEQ / SC_T;
;             v2u RAh[2][4], RBh[2][4]; f32x4 RAw[2], RBw[2];
;             ST_LOAD(RA, 0); ST_LOAD(RB, 1);
.LBB0_1758:
	s_mul_i32 s70, s52, 4
	s_mul_i32 s65, s96, 4
	s_add_u32 s65, s65, s80
	s_sub_u32 s65, s65, 4
	s_sub_u32 s65, s65, s70
	s_mov_b32 s66, 1
	s_mov_b32 s67, 0
	s_mov_b32 s68, 0
	s_mov_b32 s69, 0
	s_mov_b32 s71, 0
	s_mov_b32 s32, 0
	s_ashr_i32 s48, s55, 6
	s_bfe_u32 s6, s55, 0x50001
	s_ashr_i32 s49, s48, 31
	s_lshl_b64 s[44:45], s[48:49], 22
	s_lshl_b32 s0, s6, 6
	s_or_b32 s44, s44, s0
	s_waitcnt vmcnt(5)
	v_mov_b32_e32 v61, s45
	v_or_b32_e32 v60, s44, v90
	v_lshl_add_u64 v[12:13], v[60:61], 0, v[108:109]
	v_lshlrev_b64 v[14:15], 1, v[12:13]
	s_lshl_b32 s0, s6, 8
	v_lshl_add_u64 v[16:17], s[12:13], 0, v[14:15]
	v_lshl_add_u64 v[0:1], v[94:95], 0, s[0:1]
	v_lshl_add_u64 v[4:5], v[96:97], 0, s[0:1]
	v_lshl_add_u64 v[8:9], v[98:99], 0, s[0:1]
	global_load_dwordx2 v[30:31], v[16:17], off
	v_lshl_add_u64 v[16:17], s[24:25], 0, v[14:15]
	v_lshl_add_u64 v[18:19], s[26:27], 0, v[14:15]
	v_lshl_add_u64 v[12:13], v[12:13], 2, s[14:15]
	global_load_dwordx4 v[0:3], v[0:1], off
	v_lshl_add_u64 v[14:15], s[16:17], 0, v[14:15]
	global_load_dwordx4 v[4:7], v[4:5], off
	s_and_b32 s0, s55, 1
	global_load_dwordx4 v[8:11], v[8:9], off
	s_nop 0
	global_load_dwordx2 v[32:33], v[16:17], off
	global_load_dwordx2 v[42:43], v[18:19], off
	s_nop 0
	global_load_dwordx4 v[16:19], v[12:13], off
	global_load_dwordx2 v[34:35], v[14:15], off
	v_lshl_add_u64 v[12:13], v[60:61], 0, v[112:113]
	v_lshlrev_b64 v[14:15], 1, v[12:13]
	v_lshl_add_u64 v[20:21], s[12:13], 0, v[14:15]
	global_load_dwordx2 v[38:39], v[20:21], off
	v_lshl_add_u64 v[20:21], s[24:25], 0, v[14:15]
	v_lshl_add_u64 v[22:23], s[26:27], 0, v[14:15]
	global_load_dwordx2 v[40:41], v[20:21], off
	global_load_dwordx2 v[36:37], v[22:23], off
	v_lshl_add_u64 v[12:13], v[12:13], 2, s[14:15]
	v_lshl_add_u64 v[20:21], s[16:17], 0, v[14:15]
	global_load_dwordx4 v[12:15], v[12:13], off
	s_nop 0
	global_load_dwordx2 v[44:45], v[20:21], off
	v_lshl_add_u64 v[20:21], v[60:61], 0, v[114:115]
	v_lshlrev_b64 v[22:23], 1, v[20:21]
	s_waitcnt vmcnt(15)
	v_lshl_add_u64 v[24:25], s[12:13], 0, v[22:23]
	global_load_dwordx2 v[64:65], v[24:25], off
	v_lshl_add_u64 v[24:25], s[24:25], 0, v[22:23]
	v_lshl_add_u64 v[26:27], s[26:27], 0, v[22:23]
	v_lshl_add_u64 v[20:21], v[20:21], 2, s[14:15]
	global_load_dwordx2 v[66:67], v[24:25], off
	global_load_dwordx2 v[58:59], v[26:27], off
	v_lshl_add_u64 v[22:23], s[16:17], 0, v[22:23]
	global_load_dwordx4 v[24:27], v[20:21], off
	global_load_dwordx2 v[68:69], v[22:23], off
	v_lshl_add_u64 v[20:21], v[60:61], 0, v[116:117]
	v_lshlrev_b64 v[22:23], 1, v[20:21]
	v_lshl_add_u64 v[28:29], s[12:13], 0, v[22:23]
	global_load_dwordx2 v[54:55], v[28:29], off
	v_lshl_add_u64 v[28:29], s[24:25], 0, v[22:23]
	v_lshl_add_u64 v[20:21], v[20:21], 2, s[14:15]
	v_lshl_add_u64 v[46:47], s[26:27], 0, v[22:23]
	global_load_dwordx2 v[56:57], v[28:29], off
	global_load_dwordx2 v[52:53], v[46:47], off
	v_lshl_add_u64 v[28:29], s[16:17], 0, v[22:23]
	global_load_dwordx4 v[20:23], v[20:21], off
	s_nop 0
	global_load_dwordx2 v[62:63], v[28:29], off
	v_or_b32_e32 v28, s0, v146
	s_lshl_b32 s33, s6, 2
	v_cmp_eq_u32_e64 s[6:7], 0, v28
	s_lshl_b64 s[46:47], s[48:49], 11
	s_add_u32 s50, s3, s33
	s_addc_u32 s51, s34, 0
	s_waitcnt vmcnt(22)
	v_lshlrev_b32_e32 v28, 16, v30
	v_and_b32_e32 v29, 0xffff0000, v30
	v_lshlrev_b32_e32 v30, 16, v31
	v_and_b32_e32 v31, 0xffff0000, v31
	s_waitcnt vmcnt(18)
	v_lshlrev_b32_e32 v74, 16, v32
	v_and_b32_e32 v75, 0xffff0000, v32
	s_waitcnt vmcnt(15)
	v_lshlrev_b32_e32 v46, 16, v34
	v_and_b32_e32 v47, 0xffff0000, v34
	v_lshlrev_b32_e32 v48, 16, v35
	v_and_b32_e32 v49, 0xffff0000, v35
	v_lshlrev_b32_e32 v32, 16, v33
	v_and_b32_e32 v33, 0xffff0000, v33
	v_pk_add_f32 v[34:35], v[48:49], -1.0 op_sel_hi:[1,0]
	v_pk_add_f32 v[72:73], v[46:47], -1.0 op_sel_hi:[1,0]
	v_pk_mul_f32 v[50:51], v[2:3], v[32:33]
	v_pk_mul_f32 v[70:71], v[0:1], v[74:75]
	v_pk_fma_f32 v[80:81], v[4:5], v[72:73], 1.0 op_sel_hi:[1,1,0]
	v_pk_fma_f32 v[34:35], v[6:7], v[34:35], 1.0 op_sel_hi:[1,1,0]
	v_pk_mul_f32 v[76:77], v[50:51], v[50:51]
	v_pk_mul_f32 v[78:79], v[70:71], v[70:71]
	v_pk_mul_f32 v[34:35], v[34:35], v[32:33]
	v_pk_mul_f32 v[32:33], v[80:81], v[74:75]
	v_pk_mov_b32 v[72:73], v[78:79], v[76:77] op_sel:[1,0]
	v_mov_b32_e32 v79, v77
	v_pk_mul_f32 v[74:75], v[32:33], v[28:29]
	v_pk_mul_f32 v[76:77], v[34:35], v[30:31]
	v_pk_mul_f32 v[74:75], v[8:9], v[74:75]
	v_pk_mul_f32 v[76:77], v[10:11], v[76:77]
	v_pk_add_f32 v[72:73], v[72:73], v[78:79]
	v_add_f32_e32 v74, v74, v75
	v_add_f32_e32 v75, v76, v77
	v_add_f32_e32 v72, v72, v73
	v_add_f32_e32 v74, v74, v75
	s_nop 0
	v_add_f32_dpp v72, v72, v72 quad_perm:[1,0,3,2] row_mask:0xf bank_mask:0xf bound_ctrl:1
	v_add_f32_dpp v74, v74, v74 quad_perm:[1,0,3,2] row_mask:0xf bank_mask:0xf bound_ctrl:1
	s_nop 0
	v_add_f32_dpp v72, v72, v72 quad_perm:[2,3,0,1] row_mask:0xf bank_mask:0xf bound_ctrl:1
	v_add_f32_dpp v74, v74, v74 quad_perm:[2,3,0,1] row_mask:0xf bank_mask:0xf bound_ctrl:1
	s_nop 0
	v_add_f32_dpp v72, v72, v72 row_half_mirror row_mask:0xf bank_mask:0xf bound_ctrl:1
	v_add_f32_dpp v74, v74, v74 row_half_mirror row_mask:0xf bank_mask:0xf bound_ctrl:1
	s_nop 0
	v_mov_b32_dpp v73, v72 row_mirror row_mask:0xf bank_mask:0xf bound_ctrl:1
	v_mov_b32_dpp v75, v74 row_mirror row_mask:0xf bank_mask:0xf bound_ctrl:1
	s_and_saveexec_b64 s[8:9], s[6:7]
	s_cbranch_execz .LBB0_1760
	v_lshl_add_u64 v[76:77], s[46:47], 0, v[88:89]
	v_lshlrev_b64 v[76:77], 7, v[76:77]
	v_lshl_add_u64 v[76:77], s[50:51], 0, v[76:77]
	v_add_f32_e32 v74, v74, v75
	global_store_dword v[76:77], v74, off

; #define GAS __attribute__((address_space(1)))
; #define LAS __attribute__((address_space(3)))
; #define LDS_WAIT() asm volatile("s_waitcnt lgkmcnt(0)" ::: "memory")
; __device__ __forceinline__ unsigned pk2(float lo, float hi) { unsigned r; asm("v_cvt_pk_bf16_f32 %0, %1, %2" : "=v"(r) : "v"(lo), "v"(hi)); return r; }
; __device__ __forceinline__ void conv_proc(f32x4 (&v)[2][8], const float* gain, int K, int Kp, int Np, int ilv, bf16* WT, LAS float* scr, int item, int lane) {
;     ...
;     const int c = lane & 7;
; #pragma unroll
;     for (int hf = 0; hf < 2; ++hf) {
; #pragma unroll
;         for (int i = 0; i < 8; ++i) { LAS float* d = scr + (8 * i + kr) * 33 + 4 * n4; d[0] = v[hf][i][0]; d[1] = v[hf][i][1]; d[2] = v[hf][i][2]; d[3] = v[hf][i][3]; }
;         LDS_WAIT(); asm volatile("" ::: "memory");
; #pragma unroll
;         for (int j = 0; j < 4; ++j) { const int nn = (lane >> 3) + 8 * j; const LAS float* sp = scr + (8 * c) * 33 + nn;
;             v4u o; o.x = pk2(sp[0 * 33], sp[1 * 33]); o.y = pk2(sp[2 * 33], sp[3 * 33]); o.z = pk2(sp[4 * 33], sp[5 * 33]); o.w = pk2(sp[6 * 33], sp[7 * 33]);
;             __builtin_nontemporal_store(o, (GAS v4u*)(WT + (size_t)(d0 + 32 * hf + nn) * Kp + k0 + 8 * c)); }
;         LDS_WAIT(); asm volatile("" ::: "memory");
;     }
; }
; __device__ __forceinline__ void rwkv_scan_phase(Frame& F, const bf16* RKV, const float* WAG, const bf16* AGB, const float* k_k, const float* k_a, const float* r_k, bf16* Y, float* BS, float* ST2) {
;     ...
;             for (int ci = 0; ci < NCH; ci += 2) {
;                 if (ci >= 1) ST_FLUSH(ci - 1);
;                 if (ci + 2 < NCH) ST_LOAD(RA, ci + 2);
;                 ST_PROC(RB, ci + 1);
;                 __syncthreads();
;                 ST_FLUSH(ci);
;                 if (ci + 3 < NCH) ST_LOAD(RB, ci + 3);
;                 if (ci + 2 < NCH) ST_PROC(RA, ci + 2);
.LBB0_1787:
	s_cmp_lt_u32 s80, 4
	s_cbranch_scc1 .Lcsap_adv
	s_cmp_eq_u32 s69, 0
	s_cbranch_scc1 .Lcsap_adv
	v_mbcnt_lo_u32_b32 v243, -1, 0
	v_mbcnt_hi_u32_b32 v243, -1, v243
	s_sub_u32 s92, s80, 5
	s_mul_i32 s92, s92, 0x2100
	s_add_u32 s92, s92, 0x19200
	s_cmp_eq_u32 s80, 4
	s_cselect_b32 s92, 0x20800, s92
	v_lshrrev_b32_e32 v241, 3, v243
	v_and_b32_e32 v242, 7, v243
	v_mul_u32_u24_e32 v243, 132, v241
	v_lshl_add_u32 v243, v242, 4, v243
	v_add_u32_e32 v238, s92, v243
	v_mul_u32_u24_e32 v243, 0x420, v242
	v_lshl_add_u32 v243, v241, 2, v243
	v_add_u32_e32 v239, s92, v243
	v_mul_lo_u32 v243, v241, s81
	v_lshl_add_u32 v240, v242, 4, v243
	s_cmp_eq_u32 s32, 1
	s_cbranch_scc0 .Lcsap_w0
	s_waitcnt vmcnt(10)
	s_branch .Lcsap_wd

; __device__ __forceinline__ void convert_mats(Frame& F, int m_lo, int m_hi, int gw, int NGW) {
;     ...
;     for (int mi = m_lo; mi < m_hi; ++mi) {
;         const MatI mt = kMats[mi]; const int cnt = (mt.Kp / 64) * (mt.Np / 64);
;         const float* src = in_ptr(F, mt.in_idx) + mt.src_off; const float* gain = mt.gain_idx >= 0 ? in_ptr(F, mt.gain_idx) + mt.gain_off : nullptr; bf16* dst = (bf16*)((unsigned char*)in_ptr(F, T_WS) + mt.dst_off);
;         while (it < base + cnt) {
;             f32x4 va[2][8], vb[2][8];
;             const int lim = base + cnt, i1 = it + NGW;
;             conv_load(src, mt.K, mt.N, mt.Np, it - base, F.lane, va);
;             if (i1 < lim) conv_load(src, mt.K, mt.N, mt.Np, i1 - base, F.lane, vb);
;             conv_proc(va, gain, mt.K, mt.Kp, mt.Np, mt.ilv, dst, scr, it - base, F.lane);
;             if (i1 < lim) conv_proc(vb, gain, mt.K, mt.Kp, mt.Np, mt.ilv, dst, scr, i1 - base, F.lane);
;             it = (i1 < lim) ? i1 + NGW : i1;
;         }
;         base += cnt;
.Lcsap_adv:
	s_mov_b32 s32, 0
	s_cmp_lt_u32 s80, 4
	s_cbranch_scc1 .Lcsa_end
	s_cmp_eq_u32 s66, 0
	s_cbranch_scc0 .Lcsa_nexttile
	s_mov_b32 s66, 1
	s_branch .Lcsa_find

; __device__ __forceinline__ void convert_mats(Frame& F, int m_lo, int m_hi, int gw, int NGW) {
;     ...
;     for (int mi = m_lo; mi < m_hi; ++mi) {
;         const MatI mt = kMats[mi]; const int cnt = (mt.Kp / 64) * (mt.Np / 64);
;         const float* src = in_ptr(F, mt.in_idx) + mt.src_off; const float* gain = mt.gain_idx >= 0 ? in_ptr(F, mt.gain_idx) + mt.gain_off : nullptr; bf16* dst = (bf16*)((unsigned char*)in_ptr(F, T_WS) + mt.dst_off);
;         while (it < base + cnt) {
.Lcsa_find:
	s_cmp_lt_u32 s67, 8
	s_cbranch_scc1 .Lcsa_setup
	s_mov_b32 s69, 0
	s_branch .Lcsa_end

.Lcsa_m6:
	s_cmp_lg_u32 s67, 6
	s_cbranch_scc1 .Lcsa_m7
	s_mov_b32 s82, 32
	s_mov_b32 s83, 0x8000000
	s_mov_b32 s84, 0x2000
	s_mov_b32 s85, 0x2c00
	s_mov_b32 s86, 0
	s_mov_b32 s87, 2816
	s_mov_b32 s88, 0x5800000
	s_mov_b32 s90, 0x1c300000
	s_mov_b32 s93, 0x204f0
	s_mov_b32 s94, 0
	s_branch .Lcsa_have
.Lcsa_m7:
	s_mov_b32 s82, 288
	s_mov_b32 s83, 0xe38e39
	s_mov_b32 s84, 0x12000
	s_mov_b32 s85, 0x1000
	s_mov_b32 s86, 0
	s_mov_b32 s87, 9216
	s_mov_b32 s88, 0x9000000
	s_mov_b32 s90, 0x4900000
	s_mov_b32 s93, 0x20418
	s_mov_b32 s89, 0x2000
	s_mov_b32 s94, 0x20410

; #define LAS __attribute__((address_space(3)))
; #define LDS_WAIT() asm volatile("s_waitcnt lgkmcnt(0)" ::: "memory")
; __device__ __forceinline__ void conv_proc(f32x4 (&v)[2][8], const float* gain, int K, int Kp, int Np, int ilv, bf16* WT, LAS float* scr, int item, int lane) {
;     ...
;     const int c = lane & 7;
; #pragma unroll
;     for (int hf = 0; hf < 2; ++hf) {
; #pragma unroll
;         for (int i = 0; i < 8; ++i) { LAS float* d = scr + (8 * i + kr) * 33 + 4 * n4; d[0] = v[hf][i][0]; d[1] = v[hf][i][1]; d[2] = v[hf][i][2]; d[3] = v[hf][i][3]; }
;         LDS_WAIT(); asm volatile("" ::: "memory");
; #pragma unroll
;         for (int j = 0; j < 4; ++j) { const int nn = (lane >> 3) + 8 * j; const LAS float* sp = scr + (8 * c) * 33 + nn;
.LBB0_1797:
	s_or_b64 exec, exec, s[60:61]
	v_add_f32_e32 v181, v181, v182
	v_rsq_f32_e32 v181, v181
	ds_write_b128 v172, v[28:31] offset:45056
	ds_write_b128 v172, v[24:27] offset:53248
	ds_write_b128 v172, v[32:35] offset:61440
	v_max_f32_e64 v28, -v181, s35
	v_pk_mul_f32 v[30:31], v[142:143], v[28:29] op_sel_hi:[1,0]
	v_pk_mul_f32 v[28:29], v[144:145], v[28:29] op_sel_hi:[1,0]
	ds_write_b128 v178, v[28:31]
	v_pk_mul_f32 v[30:31], v[30:31], v[140:141] neg_lo:[1,0] neg_hi:[1,0]
	v_pk_mul_f32 v[28:29], v[28:29], v[138:139] neg_lo:[1,0] neg_hi:[1,0]
	ds_write_b128 v179, v[28:31]
	s_and_saveexec_b64 s[60:61], s[8:9]
	v_lshlrev_b32_e32 v28, 16, v64
	v_and_b32_e32 v29, 0xffff0000, v64
	v_lshlrev_b32_e32 v30, 16, v65
	v_and_b32_e32 v31, 0xffff0000, v65
	ds_write_b128 v180, v[28:31]
	s_or_b64 exec, exec, s[60:61]
	s_waitcnt lgkmcnt(0)
	s_barrier
	s_cmp_lt_u32 s80, 4
	s_cbranch_scc1 .Lcsbp_adv
	s_cmp_eq_u32 s69, 0
	s_cbranch_scc1 .Lcsbp_adv
	v_mbcnt_lo_u32_b32 v243, -1, 0
	v_mbcnt_hi_u32_b32 v243, -1, v243
	s_sub_u32 s92, s80, 5
	s_mul_i32 s92, s92, 0x2100
	s_add_u32 s92, s92, 0x19200
	s_cmp_eq_u32 s80, 4
	s_cselect_b32 s92, 0x20800, s92
	v_lshrrev_b32_e32 v241, 3, v243
	v_and_b32_e32 v242, 7, v243
	v_mul_u32_u24_e32 v243, 132, v241
	v_lshl_add_u32 v243, v242, 4, v243
	v_add_u32_e32 v238, s92, v243
	v_mul_u32_u24_e32 v243, 0x420, v242
	v_lshl_add_u32 v243, v241, 2, v243
	v_add_u32_e32 v239, s92, v243
	v_mul_lo_u32 v243, v241, s81
	v_lshl_add_u32 v240, v242, 4, v243
	s_cmp_eq_u32 s32, 1
	s_cbranch_scc0 .Lcsbp_w0
	s_waitcnt vmcnt(10)
	s_branch .Lcsbp_wd

; #define LAS __attribute__((address_space(3)))
; __device__ __forceinline__ void conv_proc(f32x4 (&v)[2][8], const float* gain, int K, int Kp, int Np, int ilv, bf16* WT, LAS float* scr, int item, int lane) {
;     const int nblk = Np / 64, kb = item / nblk, nb = item % nblk, k0 = 64 * kb, n0 = 64 * nb;
;     const int d0 = ilv ? (((n0 % ilv) >> 7) * 256 + (n0 / ilv) * 128 + ((n0 % ilv) & 127)) : n0;
;     const int kr = lane >> 3, n4 = lane & 7;
;     if (gain) {
; #pragma unroll
;         for (int i = 0; i < 8; ++i) { const int k = k0 + 8 * i + kr; const float g = k < K ? gain[k] : 0.f; v[0][i] *= g; v[1][i] *= g; } }
;     const int c = lane & 7;
; #pragma unroll
;     for (int hf = 0; hf < 2; ++hf) {
; #pragma unroll
;         for (int i = 0; i < 8; ++i) { LAS float* d = scr + (8 * i + kr) * 33 + 4 * n4; d[0] = v[hf][i][0]; d[1] = v[hf][i][1]; d[2] = v[hf][i][2]; d[3] = v[hf][i][3]; }
.LBB0_1812:
	s_cmp_lt_u32 s80, 4
	s_cbranch_scc1 .Lcsd_dskip
.Lcsd_dloop:
	s_cmp_eq_u32 s69, 0
	s_cbranch_scc1 .Lcsdp_adv
	v_mbcnt_lo_u32_b32 v243, -1, 0
	v_mbcnt_hi_u32_b32 v243, -1, v243
	s_sub_u32 s92, s80, 5
	s_mul_i32 s92, s92, 0x2100
	s_add_u32 s92, s92, 0x19200
	s_cmp_eq_u32 s80, 4
	s_cselect_b32 s92, 0x20800, s92
	v_lshrrev_b32_e32 v241, 3, v243
	v_and_b32_e32 v242, 7, v243
	v_mul_u32_u24_e32 v243, 132, v241
	v_lshl_add_u32 v243, v242, 4, v243
	v_add_u32_e32 v238, s92, v243
	v_mul_u32_u24_e32 v243, 0x420, v242
	v_lshl_add_u32 v243, v241, 2, v243
	v_add_u32_e32 v239, s92, v243
	v_mul_lo_u32 v243, v241, s81
	v_lshl_add_u32 v240, v242, 4, v243
	s_waitcnt vmcnt(0)
	s_cmp_eq_u32 s71, 0
	s_cbranch_scc1 .Lcsdp_nogain
	v_pk_mul_f32 v[188:189], v[188:189], v[220:221] op_sel_hi:[1,0]
	v_pk_mul_f32 v[190:191], v[190:191], v[220:221] op_sel_hi:[1,0]
	v_pk_mul_f32 v[192:193], v[192:193], v[220:221] op_sel:[0,1] op_sel_hi:[1,1]
	v_pk_mul_f32 v[194:195], v[194:195], v[220:221] op_sel:[0,1] op_sel_hi:[1,1]
	v_pk_mul_f32 v[196:197], v[196:197], v[222:223] op_sel_hi:[1,0]
	v_pk_mul_f32 v[198:199], v[198:199], v[222:223] op_sel_hi:[1,0]
	v_pk_mul_f32 v[200:201], v[200:201], v[222:223] op_sel:[0,1] op_sel_hi:[1,1]
	v_pk_mul_f32 v[202:203], v[202:203], v[222:223] op_sel:[0,1] op_sel_hi:[1,1]
	v_pk_mul_f32 v[204:205], v[204:205], v[224:225] op_sel_hi:[1,0]
	v_pk_mul_f32 v[206:207], v[206:207], v[224:225] op_sel_hi:[1,0]
	v_pk_mul_f32 v[208:209], v[208:209], v[224:225] op_sel:[0,1] op_sel_hi:[1,1]
	v_pk_mul_f32 v[210:211], v[210:211], v[224:225] op_sel:[0,1] op_sel_hi:[1,1]
	v_pk_mul_f32 v[212:213], v[212:213], v[226:227] op_sel_hi:[1,0]
	v_pk_mul_f32 v[214:215], v[214:215], v[226:227] op_sel_hi:[1,0]
	v_pk_mul_f32 v[216:217], v[216:217], v[226:227] op_sel:[0,1] op_sel_hi:[1,1]
	v_pk_mul_f32 v[218:219], v[218:219], v[226:227] op_sel:[0,1] op_sel_hi:[1,1]

; #define LAS __attribute__((address_space(3)))
;     __device__ __forceinline__ void ids() { lane = fresh_lane(); tid = wave * 64 + lane; }
; __device__ __forceinline__ void convert_mats(Frame& F, int m_lo, int m_hi, int gw, int NGW) {
;     LAS float* scr = (LAS float*)(F.lds + F.wave * 16384);
;     int it = gw, base = 0;
;     for (int mi = m_lo; mi < m_hi; ++mi) {
;         const MatI mt = kMats[mi]; const int cnt = (mt.Kp / 64) * (mt.Np / 64);
;         const float* src = in_ptr(F, mt.in_idx) + mt.src_off; const float* gain = mt.gain_idx >= 0 ? in_ptr(F, mt.gain_idx) + mt.gain_off : nullptr; bf16* dst = (bf16*)((unsigned char*)in_ptr(F, T_WS) + mt.dst_off);
;         while (it < base + cnt) {
;             f32x4 va[2][8], vb[2][8];
;             const int lim = base + cnt, i1 = it + NGW;
;             conv_load(src, mt.K, mt.N, mt.Np, it - base, F.lane, va);
;             if (i1 < lim) conv_load(src, mt.K, mt.N, mt.Np, i1 - base, F.lane, vb);
;             conv_proc(va, gain, mt.K, mt.Kp, mt.Np, mt.ilv, dst, scr, it - base, F.lane);
;             if (i1 < lim) conv_proc(vb, gain, mt.K, mt.Kp, mt.Np, mt.ilv, dst, scr, i1 - base, F.lane);
;             it = (i1 < lim) ? i1 + NGW : i1;
; template <int L> __device__ __forceinline__ void layer_phases(Frame& F, const int lo, const int hi, const XcdBarrier& bar, const int bid) {
;     ...
;                 } else if constexpr (L == 1) { F.ids(); convert_mats(F, 27, 29, ci * NWAVES + F.wave, nidle * NWAVES); }
.LBB0_2066:
	s_andn2_b64 vcc, exec, s[0:1]
	s_cbranch_vccnz .LBB0_2182
	v_mbcnt_lo_u32_b32 v182, -1, 0
	v_mbcnt_hi_u32_b32 v182, -1, v182
	v_lshrrev_b32_e32 v183, 3, v182
	v_and_b32_e32 v184, 7, v182
	s_lshl_b32 s4, s80, 14
	v_mul_u32_u24_e32 v0, 132, v183
	v_lshl_add_u32 v0, v184, 4, v0
	v_add_u32_e32 v172, s4, v0
	v_add_u32_e32 v173, 0x420, v172
	v_add_u32_e32 v174, 0x840, v172
	v_add_u32_e32 v175, 0xc60, v172
	v_add_u32_e32 v176, 0x1080, v172
	v_add_u32_e32 v177, 0x14a0, v172
	v_add_u32_e32 v178, 0x18c0, v172
	v_add_u32_e32 v179, 0x1ce0, v172
	v_mul_u32_u24_e32 v0, 0x420, v184
	v_lshl_add_u32 v0, v183, 2, v0
	v_add_u32_e32 v180, s4, v0
	v_lshlrev_b32_e32 v181, 2, v183
	s_lshl_b32 s20, s33, 3
	s_add_u32 s20, s20, s80
	s_lshl_b32 s21, s3, 3
	s_mov_b32 s22, 0
	s_add_i32 s4, 0, 0x20520
	v_mov_b32_e32 v0, s4
	ds_read_b64 v[2:3], v0
	s_waitcnt lgkmcnt(0)
	s_nop 0
	v_readfirstlane_b32 s58, v2
	v_readfirstlane_b32 s59, v3
	s_add_u32 s23, s22, 0x400
	s_cmp_ge_u32 s20, s23
	s_cbranch_scc1 .Lcvc_m28_done
	s_add_i32 s4, 0, 0x20420
	v_mov_b32_e32 v0, s4
	ds_read_b64 v[2:3], v0
	s_waitcnt lgkmcnt(0)
	s_nop 0
	v_readfirstlane_b32 s24, v2
	v_readfirstlane_b32 s25, v3
	s_add_u32 s24, s24, 0x1000000
	s_addc_u32 s25, s25, 0
	s_add_u32 s28, s58, 0x9900000
	s_addc_u32 s29, s59, 0
	s_mov_b32 s30, 0x2000
	s_mov_b32 s31, 0x1000
	s_mov_b32 s34, 0x8000000
	s_mov_b32 s35, 32
	s_mov_b32 s36, 0
	v_mul_lo_u32 v0, v183, s30
	v_lshl_add_u32 v160, v184, 4, v0
	v_add_u32_e32 v161, 0x10000, v160
	v_add_u32_e32 v162, 0x20000, v160
	v_add_u32_e32 v163, 0x30000, v160
	v_add_u32_e32 v164, 0x40000, v160
	v_add_u32_e32 v165, 0x50000, v160
	v_add_u32_e32 v166, 0x60000, v160
	v_add_u32_e32 v167, 0x70000, v160
	v_mul_lo_u32 v0, v183, s31
	v_lshl_add_u32 v168, v184, 4, v0
	v_add_u32_e32 v169, 0x8000, v168
	v_add_u32_e32 v170, 0x10000, v168
	v_add_u32_e32 v171, 0x18000, v168

; __device__ __forceinline__ void convert_mats(Frame& F, int m_lo, int m_hi, int gw, int NGW) {
;     ...
;     for (int mi = m_lo; mi < m_hi; ++mi) {
;         const MatI mt = kMats[mi]; const int cnt = (mt.Kp / 64) * (mt.Np / 64);
;         const float* src = in_ptr(F, mt.in_idx) + mt.src_off; const float* gain = mt.gain_idx >= 0 ? in_ptr(F, mt.gain_idx) + mt.gain_off : nullptr; bf16* dst = (bf16*)((unsigned char*)in_ptr(F, T_WS) + mt.dst_off);
;         while (it < base + cnt) {
;             f32x4 va[2][8], vb[2][8];
;             const int lim = base + cnt, i1 = it + NGW;
;             conv_load(src, mt.K, mt.N, mt.Np, it - base, F.lane, va);
;             if (i1 < lim) conv_load(src, mt.K, mt.N, mt.Np, i1 - base, F.lane, vb);
;             conv_proc(va, gain, mt.K, mt.Kp, mt.Np, mt.ilv, dst, scr, it - base, F.lane);
;             if (i1 < lim) conv_proc(vb, gain, mt.K, mt.Kp, mt.Np, mt.ilv, dst, scr, i1 - base, F.lane);
;             it = (i1 < lim) ? i1 + NGW : i1;
.Lcvc_m28_done:
	s_mov_b32 s22, s23
	s_add_u32 s23, s22, 0x1600
	s_cmp_ge_u32 s20, s23
	s_cbranch_scc1 .Lcvc_m29_done
	s_add_i32 s4, 0, 0x204d8
	v_mov_b32_e32 v0, s4
	ds_read_b64 v[2:3], v0
	s_waitcnt lgkmcnt(0)
	s_nop 0
	v_readfirstlane_b32 s24, v2
	v_readfirstlane_b32 s25, v3
	s_add_u32 s24, s24, 0x10800000
	s_addc_u32 s25, s25, 0
	s_add_i32 s4, 0, 0x204d0
	v_mov_b32_e32 v0, s4
	ds_read_b64 v[2:3], v0
	s_waitcnt lgkmcnt(0)
	s_nop 0
	v_readfirstlane_b32 s26, v2
	v_readfirstlane_b32 s27, v3
	s_add_u32 s26, s26, 0x6000
	s_addc_u32 s27, s27, 0
	s_add_u32 s28, s58, 0x16b00000
	s_addc_u32 s29, s59, 0
	s_mov_b32 s30, 0xb000
	s_mov_b32 s31, 0x1000
	s_mov_b32 s34, 0x1745d18
	s_mov_b32 s35, 176
	s_mov_b32 s36, 5632
	v_mul_lo_u32 v0, v183, s30
	v_lshl_add_u32 v160, v184, 4, v0
	v_add_u32_e32 v161, 0x58000, v160
	v_add_u32_e32 v162, 0xb0000, v160
	v_add_u32_e32 v163, 0x108000, v160
	v_add_u32_e32 v164, 0x160000, v160
	v_add_u32_e32 v165, 0x1b8000, v160
	v_add_u32_e32 v166, 0x210000, v160
	v_add_u32_e32 v167, 0x268000, v160
	v_mul_lo_u32 v0, v183, s31
	v_lshl_add_u32 v168, v184, 4, v0
	v_add_u32_e32 v169, 0x8000, v168
	v_add_u32_e32 v170, 0x10000, v168
	v_add_u32_e32 v171, 0x18000, v168

; #define LAS __attribute__((address_space(3)))
;     __device__ __forceinline__ void ids() { lane = fresh_lane(); tid = wave * 64 + lane; }
; __device__ __forceinline__ void convert_mats(Frame& F, int m_lo, int m_hi, int gw, int NGW) {
;     LAS float* scr = (LAS float*)(F.lds + F.wave * 16384);
;     int it = gw, base = 0;
;     for (int mi = m_lo; mi < m_hi; ++mi) {
;         const MatI mt = kMats[mi]; const int cnt = (mt.Kp / 64) * (mt.Np / 64);
;         const float* src = in_ptr(F, mt.in_idx) + mt.src_off; const float* gain = mt.gain_idx >= 0 ? in_ptr(F, mt.gain_idx) + mt.gain_off : nullptr; bf16* dst = (bf16*)((unsigned char*)in_ptr(F, T_WS) + mt.dst_off);
;         while (it < base + cnt) {
;             f32x4 va[2][8], vb[2][8];
;             const int lim = base + cnt, i1 = it + NGW;
;             conv_load(src, mt.K, mt.N, mt.Np, it - base, F.lane, va);
;             if (i1 < lim) conv_load(src, mt.K, mt.N, mt.Np, i1 - base, F.lane, vb);
;             conv_proc(va, gain, mt.K, mt.Kp, mt.Np, mt.ilv, dst, scr, it - base, F.lane);
;             if (i1 < lim) conv_proc(vb, gain, mt.K, mt.Kp, mt.Np, mt.ilv, dst, scr, i1 - base, F.lane);
;             it = (i1 < lim) ? i1 + NGW : i1;
; template <int L> __device__ __forceinline__ void layer_phases(Frame& F, const int lo, const int hi, const XcdBarrier& bar, const int bid) {
;     ...
;                 else if constexpr (L == 2) { F.ids(); convert_mats(F, 29, 32, ci * NWAVES + F.wave, nidle * NWAVES); }
.LBB0_2842:
	s_andn2_b64 vcc, exec, s[0:1]
	s_cbranch_vccnz .LBB0_2958
	v_mbcnt_lo_u32_b32 v182, -1, 0
	v_mbcnt_hi_u32_b32 v182, -1, v182
	v_lshrrev_b32_e32 v183, 3, v182
	v_and_b32_e32 v184, 7, v182
	s_lshl_b32 s4, s80, 14
	v_mul_u32_u24_e32 v0, 132, v183
	v_lshl_add_u32 v0, v184, 4, v0
	v_add_u32_e32 v172, s4, v0
	v_add_u32_e32 v173, 0x420, v172
	v_add_u32_e32 v174, 0x840, v172
	v_add_u32_e32 v175, 0xc60, v172
	v_add_u32_e32 v176, 0x1080, v172
	v_add_u32_e32 v177, 0x14a0, v172
	v_add_u32_e32 v178, 0x18c0, v172
	v_add_u32_e32 v179, 0x1ce0, v172
	v_mul_u32_u24_e32 v0, 0x420, v184
	v_lshl_add_u32 v0, v183, 2, v0
	v_add_u32_e32 v180, s4, v0
	v_lshlrev_b32_e32 v181, 2, v183
	s_lshl_b32 s20, s33, 3
	s_add_u32 s20, s20, s80
	s_lshl_b32 s21, s3, 3
	s_mov_b32 s22, 0
	s_add_i32 s4, 0, 0x20520
	v_mov_b32_e32 v0, s4
	ds_read_b64 v[2:3], v0
	s_waitcnt lgkmcnt(0)
	s_nop 0
	v_readfirstlane_b32 s58, v2
	v_readfirstlane_b32 s59, v3
	s_add_u32 s23, s22, 0x400
	s_cmp_ge_u32 s20, s23
	s_cbranch_scc1 .Lcvd_m26_done
	s_add_i32 s4, 0, 0x20508
	v_mov_b32_e32 v0, s4
	ds_read_b64 v[2:3], v0
	s_waitcnt lgkmcnt(0)
	s_nop 0
	v_readfirstlane_b32 s24, v2
	v_readfirstlane_b32 s25, v3
	s_add_u32 s24, s24, 0x2000000
	s_addc_u32 s25, s25, 0
	s_add_i32 s4, 0, 0x20500
	v_mov_b32_e32 v0, s4
	ds_read_b64 v[2:3], v0
	s_waitcnt lgkmcnt(0)
	s_nop 0
	v_readfirstlane_b32 s26, v2
	v_readfirstlane_b32 s27, v3
	s_add_u32 s26, s26, 0x4000
	s_addc_u32 s27, s27, 0
	s_add_u32 s28, s58, 0x1ff00000
	s_addc_u32 s29, s59, 0
	s_mov_b32 s30, 0x2000
	s_mov_b32 s31, 0x1000
	s_mov_b32 s34, 0x8000000
	s_mov_b32 s35, 32
	s_mov_b32 s36, 0
	v_mul_lo_u32 v0, v183, s30
	v_lshl_add_u32 v160, v184, 4, v0
	v_add_u32_e32 v161, 0x10000, v160
	v_add_u32_e32 v162, 0x20000, v160
	v_add_u32_e32 v163, 0x30000, v160
	v_add_u32_e32 v164, 0x40000, v160
	v_add_u32_e32 v165, 0x50000, v160
	v_add_u32_e32 v166, 0x60000, v160
	v_add_u32_e32 v167, 0x70000, v160
	v_mul_lo_u32 v0, v183, s31
	v_lshl_add_u32 v168, v184, 4, v0
	v_add_u32_e32 v169, 0x8000, v168
	v_add_u32_e32 v170, 0x10000, v168
	v_add_u32_e32 v171, 0x18000, v168
